# prep weight tiles: two tiles' row loads in flight at once (next tile requested before waiting for the current one; exact wait count when a tile lies in the zero padding)
# speedup vs baseline: 1.0029x; 1.0029x over previous
.LBB0_470:
	v_or_b32_e32 v0, s21, v3
	s_cmp_lt_i32 s28, 0
	v_cmp_le_i32_e32 vcc, s23, v0
	s_cselect_b64 s[4:5], -1, 0
	s_waitcnt lgkmcnt(0)
	v_add_u32_e32 v1, s28, v3
	v_add_u32_e32 v0, s24, v0
	s_mul_i32 s27, s27, s25
	v_cndmask_b32_e64 v0, v1, v0, s[4:5]
	s_sub_i32 s12, s22, s27
	v_ashrrev_i32_e32 v1, 31, v0
	s_lshl_b32 s12, s12, 6
	v_lshl_add_u64 v[0:1], v[0:1], 2, s[10:11]
	s_add_u32 s4, s2, s6
	s_addc_u32 s5, s3, s7
	v_add_u32_e32 v148, s21, v18
	v_ashrrev_i32_e32 v151, 31, v148
	v_mad_u64_u32 v[148:149], s[18:19], v148, s20, 0
	v_mov_b32_e32 v150, v149
	v_mad_u64_u32 v[150:151], s[18:19], v151, s20, v[150:151]
	v_mov_b32_e32 v149, v150
	v_lshl_add_u64 v[148:149], v[148:149], 1, s[4:5]
	s_ashr_i32 s13, s12, 31
	v_lshl_add_u64 v[148:149], s[12:13], 1, v[148:149]
	v_lshl_add_u64 v[144:145], v[148:149], 0, v[192:193]
	s_cmp_eq_u32 s98, 0
	s_cbranch_scc0 .Lcvt_issB
	v_mov_b32_e32 v128, 0
	v_mov_b32_e32 v129, 0
	v_mov_b32_e32 v130, 0
	v_mov_b32_e32 v131, 0
	v_mov_b32_e32 v132, 0
	v_mov_b32_e32 v133, 0
	v_mov_b32_e32 v134, 0
	v_mov_b32_e32 v135, 0
	s_mov_b64 s[18:19], exec
	s_mov_b32 s99, 0
	s_andn2_b64 exec, exec, vcc
	s_cbranch_execz .Lcvt_joinA
	s_mov_b32 s99, 1
	v_add_u32_e32 v80, s12, v2
	v_ashrrev_i32_e32 v81, 31, v80
	v_mul_lo_u32 v81, s8, v81
	v_mul_lo_u32 v84, s9, v80
	v_mad_u64_u32 v[82:83], s[4:5], s8, v80, 0
	v_add3_u32 v83, v83, v81, v84
	v_lshl_add_u64 v[82:83], v[82:83], 2, v[0:1]
	global_load_dword v128, v[82:83], off
	v_add_u32_e32 v86, 8, v80
	v_ashrrev_i32_e32 v87, 31, v86
	v_mul_lo_u32 v87, s8, v87
	v_mul_lo_u32 v90, s9, v86
	v_mad_u64_u32 v[88:89], s[4:5], s8, v86, 0
	v_add3_u32 v89, v89, v87, v90
	v_lshl_add_u64 v[88:89], v[88:89], 2, v[0:1]
	global_load_dword v129, v[88:89], off
	v_add_u32_e32 v92, s12, v6
	v_ashrrev_i32_e32 v93, 31, v92
	v_mul_lo_u32 v93, s8, v93
	v_mul_lo_u32 v96, s9, v92
	v_mad_u64_u32 v[94:95], s[4:5], s8, v92, 0
	v_add3_u32 v95, v95, v93, v96
	v_lshl_add_u64 v[94:95], v[94:95], 2, v[0:1]
	global_load_dword v130, v[94:95], off
	v_add_u32_e32 v98, s12, v8
	v_ashrrev_i32_e32 v99, 31, v98
	v_mul_lo_u32 v99, s8, v99
	v_mul_lo_u32 v102, s9, v98
	v_mad_u64_u32 v[100:101], s[4:5], s8, v98, 0
	v_add3_u32 v101, v101, v99, v102
	v_lshl_add_u64 v[100:101], v[100:101], 2, v[0:1]
	global_load_dword v131, v[100:101], off
	v_add_u32_e32 v104, s12, v10
	v_ashrrev_i32_e32 v105, 31, v104
	v_mul_lo_u32 v105, s8, v105
	v_mul_lo_u32 v108, s9, v104
	v_mad_u64_u32 v[106:107], s[4:5], s8, v104, 0
	v_add3_u32 v107, v107, v105, v108
	v_lshl_add_u64 v[106:107], v[106:107], 2, v[0:1]
	global_load_dword v132, v[106:107], off
	v_add_u32_e32 v110, s12, v12
	v_ashrrev_i32_e32 v111, 31, v110
	v_mul_lo_u32 v111, s8, v111
	v_mul_lo_u32 v114, s9, v110
	v_mad_u64_u32 v[112:113], s[4:5], s8, v110, 0
	v_add3_u32 v113, v113, v111, v114
	v_lshl_add_u64 v[112:113], v[112:113], 2, v[0:1]
	global_load_dword v133, v[112:113], off
	v_add_u32_e32 v116, s12, v14
	v_ashrrev_i32_e32 v117, 31, v116
	v_mul_lo_u32 v117, s8, v117
	v_mul_lo_u32 v120, s9, v116
	v_mad_u64_u32 v[118:119], s[4:5], s8, v116, 0
	v_add3_u32 v119, v119, v117, v120
	v_lshl_add_u64 v[118:119], v[118:119], 2, v[0:1]
	global_load_dword v134, v[118:119], off
	v_add_u32_e32 v122, s12, v16
	v_ashrrev_i32_e32 v123, 31, v122
	v_mul_lo_u32 v123, s8, v123
	v_mul_lo_u32 v126, s9, v122
	v_mad_u64_u32 v[124:125], s[4:5], s8, v122, 0
	v_add3_u32 v125, v125, v123, v126
	v_lshl_add_u64 v[124:125], v[124:125], 2, v[0:1]
	global_load_dword v135, v[124:125], off

.Lcvt_issB:
	v_mov_b32_e32 v136, 0
	v_mov_b32_e32 v137, 0
	v_mov_b32_e32 v138, 0
	v_mov_b32_e32 v139, 0
	v_mov_b32_e32 v140, 0
	v_mov_b32_e32 v141, 0
	v_mov_b32_e32 v142, 0
	v_mov_b32_e32 v143, 0
	s_mov_b64 s[18:19], exec
	s_mov_b32 s99, 0
	s_andn2_b64 exec, exec, vcc
	s_cbranch_execz .Lcvt_joinB
	s_mov_b32 s99, 1
	v_add_u32_e32 v80, s12, v2
	v_ashrrev_i32_e32 v81, 31, v80
	v_mul_lo_u32 v81, s8, v81
	v_mul_lo_u32 v84, s9, v80
	v_mad_u64_u32 v[82:83], s[4:5], s8, v80, 0
	v_add3_u32 v83, v83, v81, v84
	v_lshl_add_u64 v[82:83], v[82:83], 2, v[0:1]
	global_load_dword v136, v[82:83], off
	v_add_u32_e32 v86, 8, v80
	v_ashrrev_i32_e32 v87, 31, v86
	v_mul_lo_u32 v87, s8, v87
	v_mul_lo_u32 v90, s9, v86
	v_mad_u64_u32 v[88:89], s[4:5], s8, v86, 0
	v_add3_u32 v89, v89, v87, v90
	v_lshl_add_u64 v[88:89], v[88:89], 2, v[0:1]
	global_load_dword v137, v[88:89], off
	v_add_u32_e32 v92, s12, v6
	v_ashrrev_i32_e32 v93, 31, v92
	v_mul_lo_u32 v93, s8, v93
	v_mul_lo_u32 v96, s9, v92
	v_mad_u64_u32 v[94:95], s[4:5], s8, v92, 0
	v_add3_u32 v95, v95, v93, v96
	v_lshl_add_u64 v[94:95], v[94:95], 2, v[0:1]
	global_load_dword v138, v[94:95], off
	v_add_u32_e32 v98, s12, v8
	v_ashrrev_i32_e32 v99, 31, v98
	v_mul_lo_u32 v99, s8, v99
	v_mul_lo_u32 v102, s9, v98
	v_mad_u64_u32 v[100:101], s[4:5], s8, v98, 0
	v_add3_u32 v101, v101, v99, v102
	v_lshl_add_u64 v[100:101], v[100:101], 2, v[0:1]
	global_load_dword v139, v[100:101], off
	v_add_u32_e32 v104, s12, v10
	v_ashrrev_i32_e32 v105, 31, v104
	v_mul_lo_u32 v105, s8, v105
	v_mul_lo_u32 v108, s9, v104
	v_mad_u64_u32 v[106:107], s[4:5], s8, v104, 0
	v_add3_u32 v107, v107, v105, v108
	v_lshl_add_u64 v[106:107], v[106:107], 2, v[0:1]
	global_load_dword v140, v[106:107], off
	v_add_u32_e32 v110, s12, v12
	v_ashrrev_i32_e32 v111, 31, v110
	v_mul_lo_u32 v111, s8, v111
	v_mul_lo_u32 v114, s9, v110
	v_mad_u64_u32 v[112:113], s[4:5], s8, v110, 0
	v_add3_u32 v113, v113, v111, v114
	v_lshl_add_u64 v[112:113], v[112:113], 2, v[0:1]
	global_load_dword v141, v[112:113], off
	v_add_u32_e32 v116, s12, v14
	v_ashrrev_i32_e32 v117, 31, v116
	v_mul_lo_u32 v117, s8, v117
	v_mul_lo_u32 v120, s9, v116
	v_mad_u64_u32 v[118:119], s[4:5], s8, v116, 0
	v_add3_u32 v119, v119, v117, v120
	v_lshl_add_u64 v[118:119], v[118:119], 2, v[0:1]
	global_load_dword v142, v[118:119], off
	v_add_u32_e32 v122, s12, v16
	v_ashrrev_i32_e32 v123, 31, v122
	v_mul_lo_u32 v123, s8, v123
	v_mul_lo_u32 v126, s9, v122
	v_mad_u64_u32 v[124:125], s[4:5], s8, v122, 0
	v_add3_u32 v125, v125, v123, v126
	v_lshl_add_u64 v[124:125], v[124:125], 2, v[0:1]
	global_load_dword v143, v[124:125], off

.Lcvt_issued:
	s_cmp_eq_u32 s101, 0
	s_cbranch_scc1 .Lcvt_first
	s_cmp_eq_u32 s99, 0
	s_cbranch_scc1 .Lcvt_w01
	s_waitcnt vmcnt(8)
	s_branch .Lcvt_w11

.Lcvt_w11:
	s_barrier
	s_cmp_eq_u32 s98, 0
	s_cbranch_scc1 .Lcvt_wB1
	ds_write_b32 v4, v128
	ds_write_b32 v5, v129
	ds_write_b32 v7, v130
	ds_write_b32 v9, v131
	ds_write_b32 v11, v132
	ds_write_b32 v13, v133
	ds_write_b32 v15, v134
	ds_write_b32 v17, v135
	s_branch .Lcvt_wdone1

.Lcvt_wdone2:
	s_waitcnt lgkmcnt(0)
	s_barrier
	ds_read2_b32 v[0:1], v19 offset1:65
	ds_read2_b32 v[22:23], v19 offset0:130 offset1:195
	v_add_u32_e32 v20, 0x400, v19
	ds_read2_b32 v[24:25], v20 offset0:4 offset1:69
	ds_read2_b32 v[26:27], v20 offset0:134 offset1:199
	s_waitcnt lgkmcnt(3)
	v_cvt_pk_bf16_f32 v20, v0, v1
	s_waitcnt lgkmcnt(2)
	v_cvt_pk_bf16_f32 v21, v22, v23
	s_waitcnt lgkmcnt(1)
	v_cvt_pk_bf16_f32 v22, v24, v25
	s_waitcnt lgkmcnt(0)
	v_cvt_pk_bf16_f32 v23, v26, v27
	global_store_dwordx4 v[146:147], v[20:23], off
	s_branch .LBB0_488
	s_nop 0
	s_nop 0
	s_nop 0
	s_nop 0
	s_nop 0
	s_nop 0
	s_nop 0
	s_nop 0
	s_nop 0
	s_nop 0
